# xbpre: residual GEMM last K-iteration peeled, its 14 useless stage-ahead LDS-DMAs fetch the tile's bf16 residual pieces (+2 extra slots via 16 KiB static LDS); epilogue DMA block and post-loop vmcnt(0
# speedup vs baseline: 1.0114x; 1.0114x over previous
.LBB0_761:
	s_add_i32 vcc_lo, s42, 2
	s_add_u32 s62, s18, s40
	s_addc_u32 s43, s19, s41
	s_add_u32 vcc_hi, s4, s40
	s_addc_u32 s63, s5, s41
	s_add_i32 s95, 0, 0x10000
	s_cmp_eq_u32 s34, s42
	s_cselect_b32 s43, s13, s43
	s_cselect_b32 s42, s12, s62
	v_add_u32_e32 v160, s95, v144
	s_cselect_b32 s63, s37, s63
	s_cselect_b32 s62, s36, vcc_hi
	s_add_i32 vcc_hi, 0, 0x14000
	ds_read_b128 v[148:151], v160
	ds_read_b128 v[152:155], v160 offset:1024
	ds_read_b128 v[156:159], v160 offset:2048
	ds_read_b128 v[166:169], v160 offset:3072
	v_add_u32_e32 v160, vcc_hi, v144
	ds_read_b128 v[170:173], v160
	ds_read_b128 v[174:177], v160 offset:1024
	ds_read_b128 v[178:181], v160 offset:2048
	ds_read_b128 v[182:185], v160 offset:3072
	v_lshl_add_u64 v[160:161], s[18:19], 0, v[140:141]
	s_add_i32 m0, s91, 0xc000
	ds_read_b128 v[186:189], v145
	ds_read_b128 v[190:193], v145 offset:1024
	ds_read_b128 v[194:197], v145 offset:2048
	ds_read_b128 v[198:201], v145 offset:3072
	ds_read_b128 v[202:205], v145 offset:4096
	ds_read_b128 v[206:209], v145 offset:5120
	ds_read_b128 v[210:213], v145 offset:6144
	ds_read_b128 v[214:217], v145 offset:7168
	global_load_lds_dwordx4 v[160:161], off
	v_lshl_add_u64 v[160:161], s[18:19], 0, v[142:143]
	s_add_i32 m0, s91, 0xe000
	s_nop 0
	global_load_lds_dwordx4 v[160:161], off
	s_waitcnt vmcnt(8)
	s_waitcnt lgkmcnt(0)
	s_barrier
	s_setprio 1
	s_waitcnt lgkmcnt(0)
	v_mfma_f32_16x16x32_bf16 v[126:129], v[148:151], v[186:189], v[126:129]
	v_mfma_f32_16x16x32_bf16 v[122:125], v[156:159], v[186:189], v[122:125]
	v_mfma_f32_16x16x32_bf16 v[118:121], v[148:151], v[194:197], v[118:121]
	v_mfma_f32_16x16x32_bf16 v[114:117], v[156:159], v[194:197], v[114:117]
	v_mfma_f32_16x16x32_bf16 v[110:113], v[148:151], v[202:205], v[110:113]
	v_mfma_f32_16x16x32_bf16 v[106:109], v[156:159], v[202:205], v[106:109]
	v_mfma_f32_16x16x32_bf16 v[102:105], v[148:151], v[210:213], v[102:105]
	v_mfma_f32_16x16x32_bf16 v[98:101], v[156:159], v[210:213], v[98:101]
	v_mfma_f32_16x16x32_bf16 v[126:129], v[152:155], v[190:193], v[126:129]
	v_mfma_f32_16x16x32_bf16 v[122:125], v[166:169], v[190:193], v[122:125]
	v_mfma_f32_16x16x32_bf16 v[118:121], v[152:155], v[198:201], v[118:121]
	v_mfma_f32_16x16x32_bf16 v[114:117], v[166:169], v[198:201], v[114:117]
	v_mfma_f32_16x16x32_bf16 v[110:113], v[152:155], v[206:209], v[110:113]
	v_mfma_f32_16x16x32_bf16 v[106:109], v[166:169], v[206:209], v[106:109]
	v_mfma_f32_16x16x32_bf16 v[102:105], v[152:155], v[214:217], v[102:105]
	v_mfma_f32_16x16x32_bf16 v[98:101], v[166:169], v[214:217], v[98:101]
	s_setprio 0
	s_setprio 1
	v_mfma_f32_16x16x32_bf16 v[66:69], v[170:173], v[186:189], v[66:69]
	v_mfma_f32_16x16x32_bf16 v[58:61], v[178:181], v[186:189], v[58:61]
	v_mfma_f32_16x16x32_bf16 v[54:57], v[170:173], v[194:197], v[54:57]
	v_mfma_f32_16x16x32_bf16 v[50:53], v[178:181], v[194:197], v[50:53]
	v_mfma_f32_16x16x32_bf16 v[46:49], v[170:173], v[202:205], v[46:49]
	v_mfma_f32_16x16x32_bf16 v[42:45], v[178:181], v[202:205], v[42:45]
	v_mfma_f32_16x16x32_bf16 v[38:41], v[170:173], v[210:213], v[38:41]
	v_mfma_f32_16x16x32_bf16 v[34:37], v[178:181], v[210:213], v[34:37]
	v_mfma_f32_16x16x32_bf16 v[66:69], v[174:177], v[190:193], v[66:69]
	v_mfma_f32_16x16x32_bf16 v[58:61], v[182:185], v[190:193], v[58:61]
	v_mfma_f32_16x16x32_bf16 v[54:57], v[174:177], v[198:201], v[54:57]
	v_mfma_f32_16x16x32_bf16 v[50:53], v[182:185], v[198:201], v[50:53]
	v_mfma_f32_16x16x32_bf16 v[46:49], v[174:177], v[206:209], v[46:49]
	v_mfma_f32_16x16x32_bf16 v[42:45], v[182:185], v[206:209], v[42:45]
	v_mfma_f32_16x16x32_bf16 v[38:41], v[174:177], v[214:217], v[38:41]
	v_mfma_f32_16x16x32_bf16 v[34:37], v[182:185], v[214:217], v[34:37]
	s_setprio 0
	s_barrier
	s_add_i32 s95, s95, s86
	v_lshl_add_u64 v[160:161], s[62:63], 0, v[0:1]
	s_mov_b32 m0, s95
	ds_read_b128 v[186:189], v145 offset:16384
	ds_read_b128 v[190:193], v145 offset:17408
	ds_read_b128 v[194:197], v145 offset:18432
	ds_read_b128 v[198:201], v145 offset:19456
	ds_read_b128 v[202:205], v145 offset:20480
	ds_read_b128 v[206:209], v145 offset:21504
	ds_read_b128 v[210:213], v145 offset:22528
	ds_read_b128 v[214:217], v145 offset:23552
	global_load_lds_dwordx4 v[160:161], off
	s_add_i32 m0, s95, 0x2000
	v_lshl_add_u64 v[222:223], s[62:63], 0, v[134:135]
	s_add_u32 s62, s62, s87
	s_addc_u32 s63, s63, 0
	s_add_i32 s95, vcc_hi, s86
	global_load_lds_dwordx4 v[222:223], off
	v_lshl_add_u64 v[224:225], s[62:63], 0, v[0:1]
	s_mov_b32 m0, s95
	v_lshl_add_u64 v[226:227], s[62:63], 0, v[134:135]
	global_load_lds_dwordx4 v[224:225], off
	s_add_i32 m0, s95, 0x2000
	v_lshl_add_u64 v[228:229], s[42:43], 0, v[130:131]
	global_load_lds_dwordx4 v[226:227], off
	s_mov_b32 m0, s91
	v_lshl_add_u64 v[230:231], s[42:43], 0, v[132:133]
	global_load_lds_dwordx4 v[228:229], off
	s_mov_b32 m0, s52
	s_nop 0
	global_load_lds_dwordx4 v[230:231], off
	s_waitcnt vmcnt(8)
	s_waitcnt lgkmcnt(0)
	s_barrier
	s_setprio 1
	s_waitcnt lgkmcnt(0)
	v_mfma_f32_16x16x32_bf16 v[94:97], v[148:151], v[186:189], v[94:97]
	v_mfma_f32_16x16x32_bf16 v[90:93], v[156:159], v[186:189], v[90:93]
	v_mfma_f32_16x16x32_bf16 v[86:89], v[148:151], v[194:197], v[86:89]
	v_mfma_f32_16x16x32_bf16 v[82:85], v[156:159], v[194:197], v[82:85]
	v_mfma_f32_16x16x32_bf16 v[78:81], v[148:151], v[202:205], v[78:81]
	v_mfma_f32_16x16x32_bf16 v[74:77], v[156:159], v[202:205], v[74:77]
	v_mfma_f32_16x16x32_bf16 v[70:73], v[148:151], v[210:213], v[70:73]
	v_mfma_f32_16x16x32_bf16 v[62:65], v[156:159], v[210:213], v[62:65]
	v_mfma_f32_16x16x32_bf16 v[94:97], v[152:155], v[190:193], v[94:97]
	v_mfma_f32_16x16x32_bf16 v[90:93], v[166:169], v[190:193], v[90:93]
	v_mfma_f32_16x16x32_bf16 v[86:89], v[152:155], v[198:201], v[86:89]
	v_mfma_f32_16x16x32_bf16 v[82:85], v[166:169], v[198:201], v[82:85]
	v_mfma_f32_16x16x32_bf16 v[78:81], v[152:155], v[206:209], v[78:81]
	v_mfma_f32_16x16x32_bf16 v[74:77], v[166:169], v[206:209], v[74:77]
	v_mfma_f32_16x16x32_bf16 v[70:73], v[152:155], v[214:217], v[70:73]
	v_mfma_f32_16x16x32_bf16 v[62:65], v[166:169], v[214:217], v[62:65]
	s_setprio 0
	s_setprio 1
	v_mfma_f32_16x16x32_bf16 v[30:33], v[170:173], v[186:189], v[30:33]
	v_mfma_f32_16x16x32_bf16 v[26:29], v[178:181], v[186:189], v[26:29]
	v_mfma_f32_16x16x32_bf16 v[22:25], v[170:173], v[194:197], v[22:25]
	v_mfma_f32_16x16x32_bf16 v[18:21], v[178:181], v[194:197], v[18:21]
	v_mfma_f32_16x16x32_bf16 v[14:17], v[170:173], v[202:205], v[14:17]
	v_mfma_f32_16x16x32_bf16 v[10:13], v[178:181], v[202:205], v[10:13]
	v_mfma_f32_16x16x32_bf16 v[6:9], v[170:173], v[210:213], v[6:9]
	v_mfma_f32_16x16x32_bf16 v[2:5], v[178:181], v[210:213], v[2:5]
	v_mfma_f32_16x16x32_bf16 v[30:33], v[174:177], v[190:193], v[30:33]
	v_mfma_f32_16x16x32_bf16 v[26:29], v[182:185], v[190:193], v[26:29]
	v_mfma_f32_16x16x32_bf16 v[22:25], v[174:177], v[198:201], v[22:25]
	v_mfma_f32_16x16x32_bf16 v[18:21], v[182:185], v[198:201], v[18:21]
	v_mfma_f32_16x16x32_bf16 v[14:17], v[174:177], v[206:209], v[14:17]
	v_mfma_f32_16x16x32_bf16 v[10:13], v[182:185], v[206:209], v[10:13]
	v_mfma_f32_16x16x32_bf16 v[6:9], v[174:177], v[214:217], v[6:9]
	v_mfma_f32_16x16x32_bf16 v[2:5], v[182:185], v[214:217], v[2:5]
	s_setprio 0
	s_barrier
	s_add_i32 s62, 0, 0x18000
	v_add_u32_e32 v165, s62, v144
	s_add_i32 s63, 0, 0x1c000
	ds_read_b128 v[148:151], v165
	ds_read_b128 v[152:155], v165 offset:1024
	ds_read_b128 v[156:159], v165 offset:2048
	ds_read_b128 v[166:169], v165 offset:3072
	v_add_u32_e32 v165, s63, v144
	ds_read_b128 v[170:173], v165
	ds_read_b128 v[174:177], v165 offset:1024
	ds_read_b128 v[178:181], v165 offset:2048
	ds_read_b128 v[182:185], v165 offset:3072
	s_add_u32 s42, s42, s87
	s_addc_u32 s43, s43, 0
	s_mov_b32 m0, s53
	v_lshl_add_u64 v[232:233], s[42:43], 0, v[130:131]
	ds_read_b128 v[186:189], v145 offset:32768
	ds_read_b128 v[190:193], v145 offset:33792
	ds_read_b128 v[194:197], v145 offset:34816
	ds_read_b128 v[198:201], v145 offset:35840
	ds_read_b128 v[202:205], v145 offset:36864
	ds_read_b128 v[206:209], v145 offset:37888
	ds_read_b128 v[210:213], v145 offset:38912
	ds_read_b128 v[214:217], v145 offset:39936
	global_load_lds_dwordx4 v[232:233], off
	v_lshl_add_u64 v[232:233], s[42:43], 0, v[132:133]
	s_mov_b32 m0, s50
	s_nop 0
	global_load_lds_dwordx4 v[232:233], off
	s_waitcnt vmcnt(8)
	s_waitcnt lgkmcnt(0)
	s_barrier
	s_setprio 1
	s_waitcnt lgkmcnt(0)
	v_mfma_f32_16x16x32_bf16 v[126:129], v[148:151], v[186:189], v[126:129]
	v_mfma_f32_16x16x32_bf16 v[122:125], v[156:159], v[186:189], v[122:125]
	v_mfma_f32_16x16x32_bf16 v[118:121], v[148:151], v[194:197], v[118:121]
	v_mfma_f32_16x16x32_bf16 v[114:117], v[156:159], v[194:197], v[114:117]
	v_mfma_f32_16x16x32_bf16 v[110:113], v[148:151], v[202:205], v[110:113]
	v_mfma_f32_16x16x32_bf16 v[106:109], v[156:159], v[202:205], v[106:109]
	v_mfma_f32_16x16x32_bf16 v[102:105], v[148:151], v[210:213], v[102:105]
	v_mfma_f32_16x16x32_bf16 v[98:101], v[156:159], v[210:213], v[98:101]
	v_mfma_f32_16x16x32_bf16 v[126:129], v[152:155], v[190:193], v[126:129]
	v_mfma_f32_16x16x32_bf16 v[122:125], v[166:169], v[190:193], v[122:125]
	v_mfma_f32_16x16x32_bf16 v[118:121], v[152:155], v[198:201], v[118:121]
	v_mfma_f32_16x16x32_bf16 v[114:117], v[166:169], v[198:201], v[114:117]
	v_mfma_f32_16x16x32_bf16 v[110:113], v[152:155], v[206:209], v[110:113]
	v_mfma_f32_16x16x32_bf16 v[106:109], v[166:169], v[206:209], v[106:109]
	v_mfma_f32_16x16x32_bf16 v[102:105], v[152:155], v[214:217], v[102:105]
	v_mfma_f32_16x16x32_bf16 v[98:101], v[166:169], v[214:217], v[98:101]
	s_setprio 0
	s_setprio 1
	v_mfma_f32_16x16x32_bf16 v[66:69], v[170:173], v[186:189], v[66:69]
	v_mfma_f32_16x16x32_bf16 v[58:61], v[178:181], v[186:189], v[58:61]
	v_mfma_f32_16x16x32_bf16 v[54:57], v[170:173], v[194:197], v[54:57]
	v_mfma_f32_16x16x32_bf16 v[50:53], v[178:181], v[194:197], v[50:53]
	v_mfma_f32_16x16x32_bf16 v[46:49], v[170:173], v[202:205], v[46:49]
	v_mfma_f32_16x16x32_bf16 v[42:45], v[178:181], v[202:205], v[42:45]
	v_mfma_f32_16x16x32_bf16 v[38:41], v[170:173], v[210:213], v[38:41]
	v_mfma_f32_16x16x32_bf16 v[34:37], v[178:181], v[210:213], v[34:37]
	v_mfma_f32_16x16x32_bf16 v[66:69], v[174:177], v[190:193], v[66:69]
	v_mfma_f32_16x16x32_bf16 v[58:61], v[182:185], v[190:193], v[58:61]
	v_mfma_f32_16x16x32_bf16 v[54:57], v[174:177], v[198:201], v[54:57]
	v_mfma_f32_16x16x32_bf16 v[50:53], v[182:185], v[198:201], v[50:53]
	v_mfma_f32_16x16x32_bf16 v[46:49], v[174:177], v[206:209], v[46:49]
	v_mfma_f32_16x16x32_bf16 v[42:45], v[182:185], v[206:209], v[42:45]
	v_mfma_f32_16x16x32_bf16 v[38:41], v[174:177], v[214:217], v[38:41]
	v_mfma_f32_16x16x32_bf16 v[34:37], v[182:185], v[214:217], v[34:37]
	s_setprio 0
	s_barrier
	s_add_i32 s42, s62, s86
	v_lshl_add_u64 v[160:161], v[160:161], 0, s[76:77]
	s_mov_b32 m0, s42
	ds_read_b128 v[186:189], v145 offset:49152
	ds_read_b128 v[190:193], v145 offset:50176
	ds_read_b128 v[194:197], v145 offset:51200
	ds_read_b128 v[198:201], v145 offset:52224
	ds_read_b128 v[202:205], v145 offset:53248
	ds_read_b128 v[206:209], v145 offset:54272
	ds_read_b128 v[210:213], v145 offset:55296
	ds_read_b128 v[214:217], v145 offset:56320
	global_load_lds_dwordx4 v[160:161], off
	v_lshl_add_u64 v[160:161], v[222:223], 0, s[76:77]
	s_add_i32 m0, s42, 0x2000
	s_add_i32 s42, s63, s86
	global_load_lds_dwordx4 v[160:161], off
	v_lshl_add_u64 v[160:161], v[224:225], 0, s[76:77]
	s_mov_b32 m0, s42
	s_nop 0
	global_load_lds_dwordx4 v[160:161], off
	v_lshl_add_u64 v[160:161], v[226:227], 0, s[76:77]
	s_add_i32 m0, s42, 0x2000
	s_nop 0
	global_load_lds_dwordx4 v[160:161], off
	v_lshl_add_u64 v[160:161], v[228:229], 0, s[76:77]
	s_mov_b32 m0, s35
	s_nop 0
	global_load_lds_dwordx4 v[160:161], off
	v_lshl_add_u64 v[160:161], v[230:231], 0, s[76:77]
	s_mov_b32 m0, s48
	s_nop 0
	global_load_lds_dwordx4 v[160:161], off
	s_waitcnt vmcnt(8)
	s_waitcnt lgkmcnt(0)
	s_barrier
	s_setprio 1
	s_waitcnt lgkmcnt(0)
	v_mfma_f32_16x16x32_bf16 v[94:97], v[148:151], v[186:189], v[94:97]
	v_mfma_f32_16x16x32_bf16 v[90:93], v[156:159], v[186:189], v[90:93]
	v_mfma_f32_16x16x32_bf16 v[86:89], v[148:151], v[194:197], v[86:89]
	v_mfma_f32_16x16x32_bf16 v[82:85], v[156:159], v[194:197], v[82:85]
	v_mfma_f32_16x16x32_bf16 v[78:81], v[148:151], v[202:205], v[78:81]
	v_mfma_f32_16x16x32_bf16 v[74:77], v[156:159], v[202:205], v[74:77]
	v_mfma_f32_16x16x32_bf16 v[70:73], v[148:151], v[210:213], v[70:73]
	v_mfma_f32_16x16x32_bf16 v[62:65], v[156:159], v[210:213], v[62:65]
	v_mfma_f32_16x16x32_bf16 v[94:97], v[152:155], v[190:193], v[94:97]
	v_mfma_f32_16x16x32_bf16 v[90:93], v[166:169], v[190:193], v[90:93]
	v_mfma_f32_16x16x32_bf16 v[86:89], v[152:155], v[198:201], v[86:89]
	v_mfma_f32_16x16x32_bf16 v[82:85], v[166:169], v[198:201], v[82:85]
	v_mfma_f32_16x16x32_bf16 v[78:81], v[152:155], v[206:209], v[78:81]
	v_mfma_f32_16x16x32_bf16 v[74:77], v[166:169], v[206:209], v[74:77]
	v_mfma_f32_16x16x32_bf16 v[70:73], v[152:155], v[214:217], v[70:73]
	v_mfma_f32_16x16x32_bf16 v[62:65], v[166:169], v[214:217], v[62:65]
	s_setprio 0
	s_setprio 1
	v_mfma_f32_16x16x32_bf16 v[30:33], v[170:173], v[186:189], v[30:33]
	v_mfma_f32_16x16x32_bf16 v[26:29], v[178:181], v[186:189], v[26:29]
	v_mfma_f32_16x16x32_bf16 v[22:25], v[170:173], v[194:197], v[22:25]
	v_mfma_f32_16x16x32_bf16 v[18:21], v[178:181], v[194:197], v[18:21]
	v_mfma_f32_16x16x32_bf16 v[14:17], v[170:173], v[202:205], v[14:17]
	v_mfma_f32_16x16x32_bf16 v[10:13], v[178:181], v[202:205], v[10:13]
	v_mfma_f32_16x16x32_bf16 v[6:9], v[170:173], v[210:213], v[6:9]
	v_mfma_f32_16x16x32_bf16 v[2:5], v[178:181], v[210:213], v[2:5]
	v_mfma_f32_16x16x32_bf16 v[30:33], v[174:177], v[190:193], v[30:33]
	v_mfma_f32_16x16x32_bf16 v[26:29], v[182:185], v[190:193], v[26:29]
	v_mfma_f32_16x16x32_bf16 v[22:25], v[174:177], v[198:201], v[22:25]
	v_mfma_f32_16x16x32_bf16 v[18:21], v[182:185], v[198:201], v[18:21]
	v_mfma_f32_16x16x32_bf16 v[14:17], v[174:177], v[206:209], v[14:17]
	v_mfma_f32_16x16x32_bf16 v[10:13], v[182:185], v[206:209], v[10:13]
	v_mfma_f32_16x16x32_bf16 v[6:9], v[174:177], v[214:217], v[6:9]
	v_mfma_f32_16x16x32_bf16 v[2:5], v[182:185], v[214:217], v[2:5]
	s_setprio 0
	s_barrier
	s_add_u32 s40, s40, 0x100
	s_addc_u32 s41, s41, 0
	v_lshl_add_u64 v[142:143], v[142:143], 0, s[74:75]
	v_lshl_add_u64 v[140:141], v[140:141], 0, s[74:75]
	s_cmp_ge_u32 vcc_lo, s34
	s_mov_b32 s42, vcc_lo
	s_cbranch_scc0 .LBB0_761
	s_lshl_b32 s98, s6, 8
	s_add_i32 s98, s98, s80
	v_or_b32_e32 v234, s98, v164
	s_lshl_b32 s98, s28, 8
	s_lshl_b32 s99, s45, 5
	s_or_b32 s98, s98, s99
	v_lshrrev_b32_e32 v236, 1, v163
	v_and_or_b32 v236, v236, 24, s98
	v_lshl_add_u32 v234, v234, 10, v236
	v_lshlrev_b32_e32 v234, 1, v234
	v_mov_b32_e32 v235, 0
	s_add_u32 s98, s96, 0x10000000
	s_addc_u32 s99, s97, 0
	v_lshl_add_u64 v[234:235], s[98:99], 0, v[234:235]
	s_add_i32 vcc_lo, s42, 2
	s_add_u32 s62, s18, s40
	s_addc_u32 s43, s19, s41
	s_add_u32 vcc_hi, s4, s40
	s_addc_u32 s63, s5, s41
	s_add_i32 s95, 0, 0x10000
	s_cmp_eq_u32 s34, s42
	s_cselect_b32 s43, s13, s43
	s_cselect_b32 s42, s12, s62
	v_add_u32_e32 v160, s95, v144
	s_cselect_b32 s63, s37, s63
	s_cselect_b32 s62, s36, vcc_hi
	s_add_i32 vcc_hi, 0, 0x14000
	ds_read_b128 v[148:151], v160
	ds_read_b128 v[152:155], v160 offset:1024
	ds_read_b128 v[156:159], v160 offset:2048
	ds_read_b128 v[166:169], v160 offset:3072
	v_add_u32_e32 v160, vcc_hi, v144
	ds_read_b128 v[170:173], v160
	ds_read_b128 v[174:177], v160 offset:1024
	ds_read_b128 v[178:181], v160 offset:2048
	ds_read_b128 v[182:185], v160 offset:3072
	v_lshl_add_u64 v[160:161], s[18:19], 0, v[140:141]
	s_add_i32 m0, s91, 0xc000
	ds_read_b128 v[186:189], v145
	ds_read_b128 v[190:193], v145 offset:1024
	ds_read_b128 v[194:197], v145 offset:2048
	ds_read_b128 v[198:201], v145 offset:3072
	ds_read_b128 v[202:205], v145 offset:4096
	ds_read_b128 v[206:209], v145 offset:5120
	ds_read_b128 v[210:213], v145 offset:6144
	ds_read_b128 v[214:217], v145 offset:7168
	global_load_lds_dwordx4 v[160:161], off
	v_lshl_add_u64 v[160:161], s[18:19], 0, v[142:143]
	s_add_i32 m0, s91, 0xe000
	s_nop 0
	global_load_lds_dwordx4 v[160:161], off
	s_waitcnt vmcnt(8)
	s_waitcnt lgkmcnt(0)
	s_barrier
	s_setprio 1
	s_waitcnt lgkmcnt(0)
	v_mfma_f32_16x16x32_bf16 v[126:129], v[148:151], v[186:189], v[126:129]
	v_mfma_f32_16x16x32_bf16 v[122:125], v[156:159], v[186:189], v[122:125]
	v_mfma_f32_16x16x32_bf16 v[118:121], v[148:151], v[194:197], v[118:121]
	v_mfma_f32_16x16x32_bf16 v[114:117], v[156:159], v[194:197], v[114:117]
	v_mfma_f32_16x16x32_bf16 v[110:113], v[148:151], v[202:205], v[110:113]
	v_mfma_f32_16x16x32_bf16 v[106:109], v[156:159], v[202:205], v[106:109]
	v_mfma_f32_16x16x32_bf16 v[102:105], v[148:151], v[210:213], v[102:105]
	v_mfma_f32_16x16x32_bf16 v[98:101], v[156:159], v[210:213], v[98:101]
	v_mfma_f32_16x16x32_bf16 v[126:129], v[152:155], v[190:193], v[126:129]
	v_mfma_f32_16x16x32_bf16 v[122:125], v[166:169], v[190:193], v[122:125]
	v_mfma_f32_16x16x32_bf16 v[118:121], v[152:155], v[198:201], v[118:121]
	v_mfma_f32_16x16x32_bf16 v[114:117], v[166:169], v[198:201], v[114:117]
	v_mfma_f32_16x16x32_bf16 v[110:113], v[152:155], v[206:209], v[110:113]
	v_mfma_f32_16x16x32_bf16 v[106:109], v[166:169], v[206:209], v[106:109]
	v_mfma_f32_16x16x32_bf16 v[102:105], v[152:155], v[214:217], v[102:105]
	v_mfma_f32_16x16x32_bf16 v[98:101], v[166:169], v[214:217], v[98:101]
	s_setprio 0
	s_setprio 1
	v_mfma_f32_16x16x32_bf16 v[66:69], v[170:173], v[186:189], v[66:69]
	v_mfma_f32_16x16x32_bf16 v[58:61], v[178:181], v[186:189], v[58:61]
	v_mfma_f32_16x16x32_bf16 v[54:57], v[170:173], v[194:197], v[54:57]
	v_mfma_f32_16x16x32_bf16 v[50:53], v[178:181], v[194:197], v[50:53]
	v_mfma_f32_16x16x32_bf16 v[46:49], v[170:173], v[202:205], v[46:49]
	v_mfma_f32_16x16x32_bf16 v[42:45], v[178:181], v[202:205], v[42:45]
	v_mfma_f32_16x16x32_bf16 v[38:41], v[170:173], v[210:213], v[38:41]
	v_mfma_f32_16x16x32_bf16 v[34:37], v[178:181], v[210:213], v[34:37]
	v_mfma_f32_16x16x32_bf16 v[66:69], v[174:177], v[190:193], v[66:69]
	v_mfma_f32_16x16x32_bf16 v[58:61], v[182:185], v[190:193], v[58:61]
	v_mfma_f32_16x16x32_bf16 v[54:57], v[174:177], v[198:201], v[54:57]
	v_mfma_f32_16x16x32_bf16 v[50:53], v[182:185], v[198:201], v[50:53]
	v_mfma_f32_16x16x32_bf16 v[46:49], v[174:177], v[206:209], v[46:49]
	v_mfma_f32_16x16x32_bf16 v[42:45], v[182:185], v[206:209], v[42:45]
	v_mfma_f32_16x16x32_bf16 v[38:41], v[174:177], v[214:217], v[38:41]
	v_mfma_f32_16x16x32_bf16 v[34:37], v[182:185], v[214:217], v[34:37]
	s_setprio 0
	s_barrier
	s_add_i32 s95, s95, s86
	v_lshl_add_u64 v[160:161], s[62:63], 0, v[0:1]
	s_mov_b32 m0, s95
	ds_read_b128 v[186:189], v145 offset:16384
	ds_read_b128 v[190:193], v145 offset:17408
	ds_read_b128 v[194:197], v145 offset:18432
	ds_read_b128 v[198:201], v145 offset:19456
	ds_read_b128 v[202:205], v145 offset:20480
	ds_read_b128 v[206:209], v145 offset:21504
	ds_read_b128 v[210:213], v145 offset:22528
	ds_read_b128 v[214:217], v145 offset:23552
	s_add_i32 m0, s91, 0x10000
	s_nop 0
	global_load_lds_dwordx4 v[234:235], off
	s_add_i32 m0, s95, 0x2000
	v_lshl_add_u64 v[222:223], s[62:63], 0, v[134:135]
	s_add_u32 s62, s62, s87
	s_addc_u32 s63, s63, 0
	s_add_i32 s95, vcc_hi, s86
	s_add_i32 m0, s91, 0x12000
	s_mov_b64 s[98:99], 0x8000
	v_lshl_add_u64 v[236:237], v[234:235], 0, s[98:99]
	global_load_lds_dwordx4 v[236:237], off
	v_lshl_add_u64 v[224:225], s[62:63], 0, v[0:1]
	s_mov_b32 m0, s95
	v_lshl_add_u64 v[226:227], s[62:63], 0, v[134:135]
	s_add_i32 m0, s91, 0x14000
	s_mov_b64 s[98:99], 0x10000
	v_lshl_add_u64 v[236:237], v[234:235], 0, s[98:99]
	global_load_lds_dwordx4 v[236:237], off
	s_add_i32 m0, s95, 0x2000
	v_lshl_add_u64 v[228:229], s[42:43], 0, v[130:131]
	s_add_i32 m0, s91, 0x16000
	s_mov_b64 s[98:99], 0x18000
	v_lshl_add_u64 v[236:237], v[234:235], 0, s[98:99]
	global_load_lds_dwordx4 v[236:237], off
	s_mov_b32 m0, s91
	v_lshl_add_u64 v[230:231], s[42:43], 0, v[132:133]
	s_add_i32 m0, s91, 0x20000
	s_mov_b64 s[98:99], 0x40000
	v_lshl_add_u64 v[236:237], v[234:235], 0, s[98:99]
	global_load_lds_dwordx4 v[236:237], off
	s_mov_b32 m0, s52
	s_nop 0
	s_add_i32 m0, s91, 0x2000
	s_mov_b64 s[98:99], 0x48000
	v_lshl_add_u64 v[236:237], v[234:235], 0, s[98:99]
	global_load_lds_dwordx4 v[236:237], off
	s_add_i32 m0, s91, 0x24000
	s_mov_b64 s[98:99], 0x50000
	v_lshl_add_u64 v[236:237], v[234:235], 0, s[98:99]
	global_load_lds_dwordx4 v[236:237], off
	s_add_i32 m0, s91, 0x26000
	s_mov_b64 s[98:99], 0x58000
	v_lshl_add_u64 v[236:237], v[234:235], 0, s[98:99]
	global_load_lds_dwordx4 v[236:237], off
	s_waitcnt vmcnt(10)
	s_waitcnt lgkmcnt(0)
	s_barrier
	s_setprio 1
	s_waitcnt lgkmcnt(0)
	v_mfma_f32_16x16x32_bf16 v[94:97], v[148:151], v[186:189], v[94:97]
	v_mfma_f32_16x16x32_bf16 v[90:93], v[156:159], v[186:189], v[90:93]
	v_mfma_f32_16x16x32_bf16 v[86:89], v[148:151], v[194:197], v[86:89]
	v_mfma_f32_16x16x32_bf16 v[82:85], v[156:159], v[194:197], v[82:85]
	v_mfma_f32_16x16x32_bf16 v[78:81], v[148:151], v[202:205], v[78:81]
	v_mfma_f32_16x16x32_bf16 v[74:77], v[156:159], v[202:205], v[74:77]
	v_mfma_f32_16x16x32_bf16 v[70:73], v[148:151], v[210:213], v[70:73]
	v_mfma_f32_16x16x32_bf16 v[62:65], v[156:159], v[210:213], v[62:65]
	v_mfma_f32_16x16x32_bf16 v[94:97], v[152:155], v[190:193], v[94:97]
	v_mfma_f32_16x16x32_bf16 v[90:93], v[166:169], v[190:193], v[90:93]
	v_mfma_f32_16x16x32_bf16 v[86:89], v[152:155], v[198:201], v[86:89]
	v_mfma_f32_16x16x32_bf16 v[82:85], v[166:169], v[198:201], v[82:85]
	v_mfma_f32_16x16x32_bf16 v[78:81], v[152:155], v[206:209], v[78:81]
	v_mfma_f32_16x16x32_bf16 v[74:77], v[166:169], v[206:209], v[74:77]
	v_mfma_f32_16x16x32_bf16 v[70:73], v[152:155], v[214:217], v[70:73]
	v_mfma_f32_16x16x32_bf16 v[62:65], v[166:169], v[214:217], v[62:65]
	s_setprio 0
	s_setprio 1
	v_mfma_f32_16x16x32_bf16 v[30:33], v[170:173], v[186:189], v[30:33]
	v_mfma_f32_16x16x32_bf16 v[26:29], v[178:181], v[186:189], v[26:29]
	v_mfma_f32_16x16x32_bf16 v[22:25], v[170:173], v[194:197], v[22:25]
	v_mfma_f32_16x16x32_bf16 v[18:21], v[178:181], v[194:197], v[18:21]
	v_mfma_f32_16x16x32_bf16 v[14:17], v[170:173], v[202:205], v[14:17]
	v_mfma_f32_16x16x32_bf16 v[10:13], v[178:181], v[202:205], v[10:13]
	v_mfma_f32_16x16x32_bf16 v[6:9], v[170:173], v[210:213], v[6:9]
	v_mfma_f32_16x16x32_bf16 v[2:5], v[178:181], v[210:213], v[2:5]
	v_mfma_f32_16x16x32_bf16 v[30:33], v[174:177], v[190:193], v[30:33]
	v_mfma_f32_16x16x32_bf16 v[26:29], v[182:185], v[190:193], v[26:29]
	v_mfma_f32_16x16x32_bf16 v[22:25], v[174:177], v[198:201], v[22:25]
	v_mfma_f32_16x16x32_bf16 v[18:21], v[182:185], v[198:201], v[18:21]
	v_mfma_f32_16x16x32_bf16 v[14:17], v[174:177], v[206:209], v[14:17]
	v_mfma_f32_16x16x32_bf16 v[10:13], v[182:185], v[206:209], v[10:13]
	v_mfma_f32_16x16x32_bf16 v[6:9], v[174:177], v[214:217], v[6:9]
	v_mfma_f32_16x16x32_bf16 v[2:5], v[182:185], v[214:217], v[2:5]
	s_setprio 0
	s_barrier
	s_add_i32 s62, 0, 0x18000
	v_add_u32_e32 v165, s62, v144
	s_add_i32 s63, 0, 0x1c000
	ds_read_b128 v[148:151], v165
	ds_read_b128 v[152:155], v165 offset:1024
	ds_read_b128 v[156:159], v165 offset:2048
	ds_read_b128 v[166:169], v165 offset:3072
	v_add_u32_e32 v165, s63, v144
	ds_read_b128 v[170:173], v165
	ds_read_b128 v[174:177], v165 offset:1024
	ds_read_b128 v[178:181], v165 offset:2048
	ds_read_b128 v[182:185], v165 offset:3072
	s_add_u32 s42, s42, s87
	s_addc_u32 s43, s43, 0
	s_mov_b32 m0, s53
	v_lshl_add_u64 v[232:233], s[42:43], 0, v[130:131]
	ds_read_b128 v[186:189], v145 offset:32768
	ds_read_b128 v[190:193], v145 offset:33792
	ds_read_b128 v[194:197], v145 offset:34816
	ds_read_b128 v[198:201], v145 offset:35840
	ds_read_b128 v[202:205], v145 offset:36864
	ds_read_b128 v[206:209], v145 offset:37888
	ds_read_b128 v[210:213], v145 offset:38912
	ds_read_b128 v[214:217], v145 offset:39936
	s_add_i32 m0, s91, 0x4000
	s_mov_b64 s[98:99], 0x100
	v_lshl_add_u64 v[236:237], v[234:235], 0, s[98:99]
	global_load_lds_dwordx4 v[236:237], off
	v_lshl_add_u64 v[232:233], s[42:43], 0, v[132:133]
	s_mov_b32 m0, s50
	s_nop 0
	s_add_i32 m0, s91, 0x6000
	s_mov_b64 s[98:99], 0x8100
	v_lshl_add_u64 v[236:237], v[234:235], 0, s[98:99]
	global_load_lds_dwordx4 v[236:237], off
	s_waitcnt vmcnt(10)
	s_waitcnt lgkmcnt(0)
	s_barrier
	s_setprio 1
	s_waitcnt lgkmcnt(0)
	v_mfma_f32_16x16x32_bf16 v[126:129], v[148:151], v[186:189], v[126:129]
	v_mfma_f32_16x16x32_bf16 v[122:125], v[156:159], v[186:189], v[122:125]
	v_mfma_f32_16x16x32_bf16 v[118:121], v[148:151], v[194:197], v[118:121]
	v_mfma_f32_16x16x32_bf16 v[114:117], v[156:159], v[194:197], v[114:117]
	v_mfma_f32_16x16x32_bf16 v[110:113], v[148:151], v[202:205], v[110:113]
	v_mfma_f32_16x16x32_bf16 v[106:109], v[156:159], v[202:205], v[106:109]
	v_mfma_f32_16x16x32_bf16 v[102:105], v[148:151], v[210:213], v[102:105]
	v_mfma_f32_16x16x32_bf16 v[98:101], v[156:159], v[210:213], v[98:101]
	v_mfma_f32_16x16x32_bf16 v[126:129], v[152:155], v[190:193], v[126:129]
	v_mfma_f32_16x16x32_bf16 v[122:125], v[166:169], v[190:193], v[122:125]
	v_mfma_f32_16x16x32_bf16 v[118:121], v[152:155], v[198:201], v[118:121]
	v_mfma_f32_16x16x32_bf16 v[114:117], v[166:169], v[198:201], v[114:117]
	v_mfma_f32_16x16x32_bf16 v[110:113], v[152:155], v[206:209], v[110:113]
	v_mfma_f32_16x16x32_bf16 v[106:109], v[166:169], v[206:209], v[106:109]
	v_mfma_f32_16x16x32_bf16 v[102:105], v[152:155], v[214:217], v[102:105]
	v_mfma_f32_16x16x32_bf16 v[98:101], v[166:169], v[214:217], v[98:101]
	s_setprio 0
	s_setprio 1
	v_mfma_f32_16x16x32_bf16 v[66:69], v[170:173], v[186:189], v[66:69]
	v_mfma_f32_16x16x32_bf16 v[58:61], v[178:181], v[186:189], v[58:61]
	v_mfma_f32_16x16x32_bf16 v[54:57], v[170:173], v[194:197], v[54:57]
	v_mfma_f32_16x16x32_bf16 v[50:53], v[178:181], v[194:197], v[50:53]
	v_mfma_f32_16x16x32_bf16 v[46:49], v[170:173], v[202:205], v[46:49]
	v_mfma_f32_16x16x32_bf16 v[42:45], v[178:181], v[202:205], v[42:45]
	v_mfma_f32_16x16x32_bf16 v[38:41], v[170:173], v[210:213], v[38:41]
	v_mfma_f32_16x16x32_bf16 v[34:37], v[178:181], v[210:213], v[34:37]
	v_mfma_f32_16x16x32_bf16 v[66:69], v[174:177], v[190:193], v[66:69]
	v_mfma_f32_16x16x32_bf16 v[58:61], v[182:185], v[190:193], v[58:61]
	v_mfma_f32_16x16x32_bf16 v[54:57], v[174:177], v[198:201], v[54:57]
	v_mfma_f32_16x16x32_bf16 v[50:53], v[182:185], v[198:201], v[50:53]
	v_mfma_f32_16x16x32_bf16 v[46:49], v[174:177], v[206:209], v[46:49]
	v_mfma_f32_16x16x32_bf16 v[42:45], v[182:185], v[206:209], v[42:45]
	v_mfma_f32_16x16x32_bf16 v[38:41], v[174:177], v[214:217], v[38:41]
	v_mfma_f32_16x16x32_bf16 v[34:37], v[182:185], v[214:217], v[34:37]
	s_setprio 0
	s_barrier
	s_add_i32 s42, s62, s86
	v_lshl_add_u64 v[160:161], v[160:161], 0, s[76:77]
	s_mov_b32 m0, s42
	ds_read_b128 v[186:189], v145 offset:49152
	ds_read_b128 v[190:193], v145 offset:50176
	ds_read_b128 v[194:197], v145 offset:51200
	ds_read_b128 v[198:201], v145 offset:52224
	ds_read_b128 v[202:205], v145 offset:53248
	ds_read_b128 v[206:209], v145 offset:54272
	ds_read_b128 v[210:213], v145 offset:55296
	ds_read_b128 v[214:217], v145 offset:56320
	s_add_i32 m0, s91, 0x18000
	s_mov_b64 s[98:99], 0x10100
	v_lshl_add_u64 v[236:237], v[234:235], 0, s[98:99]
	global_load_lds_dwordx4 v[236:237], off
	v_lshl_add_u64 v[160:161], v[222:223], 0, s[76:77]
	s_add_i32 m0, s42, 0x2000
	s_add_i32 s42, s63, s86
	s_add_i32 m0, s91, 0x1a000
	s_mov_b64 s[98:99], 0x18100
	v_lshl_add_u64 v[236:237], v[234:235], 0, s[98:99]
	global_load_lds_dwordx4 v[236:237], off
	v_lshl_add_u64 v[160:161], v[224:225], 0, s[76:77]
	s_mov_b32 m0, s42
	s_nop 0
	s_add_i32 m0, s91, 0x1c000
	s_mov_b64 s[98:99], 0x40100
	v_lshl_add_u64 v[236:237], v[234:235], 0, s[98:99]
	global_load_lds_dwordx4 v[236:237], off
	v_lshl_add_u64 v[160:161], v[226:227], 0, s[76:77]
	s_add_i32 m0, s42, 0x2000
	s_nop 0
	s_add_i32 m0, s91, 0x1e000
	s_mov_b64 s[98:99], 0x48100
	v_lshl_add_u64 v[236:237], v[234:235], 0, s[98:99]
	global_load_lds_dwordx4 v[236:237], off
	v_lshl_add_u64 v[160:161], v[228:229], 0, s[76:77]
	s_mov_b32 m0, s35
	s_nop 0
	s_add_i32 m0, s91, 0x8000
	s_mov_b64 s[98:99], 0x50100
	v_lshl_add_u64 v[236:237], v[234:235], 0, s[98:99]
	global_load_lds_dwordx4 v[236:237], off
	v_lshl_add_u64 v[160:161], v[230:231], 0, s[76:77]
	s_mov_b32 m0, s48
	s_nop 0
	s_add_i32 m0, s91, 0xa000
	s_mov_b64 s[98:99], 0x58100
	v_lshl_add_u64 v[236:237], v[234:235], 0, s[98:99]
	global_load_lds_dwordx4 v[236:237], off
	s_waitcnt vmcnt(16)
	s_waitcnt lgkmcnt(0)
	s_barrier
	s_setprio 1
	s_waitcnt lgkmcnt(0)
	v_mfma_f32_16x16x32_bf16 v[94:97], v[148:151], v[186:189], v[94:97]
	v_mfma_f32_16x16x32_bf16 v[90:93], v[156:159], v[186:189], v[90:93]
	v_mfma_f32_16x16x32_bf16 v[86:89], v[148:151], v[194:197], v[86:89]
	v_mfma_f32_16x16x32_bf16 v[82:85], v[156:159], v[194:197], v[82:85]
	v_mfma_f32_16x16x32_bf16 v[78:81], v[148:151], v[202:205], v[78:81]
	v_mfma_f32_16x16x32_bf16 v[74:77], v[156:159], v[202:205], v[74:77]
	v_mfma_f32_16x16x32_bf16 v[70:73], v[148:151], v[210:213], v[70:73]
	v_mfma_f32_16x16x32_bf16 v[62:65], v[156:159], v[210:213], v[62:65]
	v_mfma_f32_16x16x32_bf16 v[94:97], v[152:155], v[190:193], v[94:97]
	v_mfma_f32_16x16x32_bf16 v[90:93], v[166:169], v[190:193], v[90:93]
	v_mfma_f32_16x16x32_bf16 v[86:89], v[152:155], v[198:201], v[86:89]
	v_mfma_f32_16x16x32_bf16 v[82:85], v[166:169], v[198:201], v[82:85]
	v_mfma_f32_16x16x32_bf16 v[78:81], v[152:155], v[206:209], v[78:81]
	v_mfma_f32_16x16x32_bf16 v[74:77], v[166:169], v[206:209], v[74:77]
	v_mfma_f32_16x16x32_bf16 v[70:73], v[152:155], v[214:217], v[70:73]
	v_mfma_f32_16x16x32_bf16 v[62:65], v[166:169], v[214:217], v[62:65]
	s_setprio 0
	s_setprio 1
	v_mfma_f32_16x16x32_bf16 v[30:33], v[170:173], v[186:189], v[30:33]
	v_mfma_f32_16x16x32_bf16 v[26:29], v[178:181], v[186:189], v[26:29]
	v_mfma_f32_16x16x32_bf16 v[22:25], v[170:173], v[194:197], v[22:25]
	v_mfma_f32_16x16x32_bf16 v[18:21], v[178:181], v[194:197], v[18:21]
	v_mfma_f32_16x16x32_bf16 v[14:17], v[170:173], v[202:205], v[14:17]
	v_mfma_f32_16x16x32_bf16 v[10:13], v[178:181], v[202:205], v[10:13]
	v_mfma_f32_16x16x32_bf16 v[6:9], v[170:173], v[210:213], v[6:9]
	v_mfma_f32_16x16x32_bf16 v[2:5], v[178:181], v[210:213], v[2:5]
	v_mfma_f32_16x16x32_bf16 v[30:33], v[174:177], v[190:193], v[30:33]
	v_mfma_f32_16x16x32_bf16 v[26:29], v[182:185], v[190:193], v[26:29]
	v_mfma_f32_16x16x32_bf16 v[22:25], v[174:177], v[198:201], v[22:25]
	v_mfma_f32_16x16x32_bf16 v[18:21], v[182:185], v[198:201], v[18:21]
	v_mfma_f32_16x16x32_bf16 v[14:17], v[174:177], v[206:209], v[14:17]
	v_mfma_f32_16x16x32_bf16 v[10:13], v[182:185], v[206:209], v[10:13]
	v_mfma_f32_16x16x32_bf16 v[6:9], v[174:177], v[214:217], v[6:9]
	v_mfma_f32_16x16x32_bf16 v[2:5], v[182:185], v[214:217], v[2:5]
	s_setprio 0
	s_barrier
	s_add_u32 s40, s40, 0x100
	s_addc_u32 s41, s41, 0
	v_lshl_add_u64 v[142:143], v[142:143], 0, s[74:75]
	v_lshl_add_u64 v[140:141], v[140:141], 0, s[74:75]
	s_cmp_ge_u32 vcc_lo, s51
	s_mov_b32 s42, vcc_lo
	s_and_b64 vcc, exec, s[10:11]
	s_cbranch_vccnz .LBB0_749
	v_mov_b32_e32 v2, 0
	s_mov_b32 s28, s61
	s_mov_b32 s6, s78
	s_mov_b64 s[4:5], s[36:37]
	s_mov_b64 s[18:19], s[12:13]
	s_mov_b32 s49, s7
	v_mov_b32_e32 v3, v2
	v_mov_b32_e32 v4, v2
	v_mov_b32_e32 v5, v2
	v_mov_b32_e32 v6, v2
	v_mov_b32_e32 v7, v2
	v_mov_b32_e32 v8, v2
	v_mov_b32_e32 v9, v2
	v_mov_b32_e32 v10, v2
	v_mov_b32_e32 v11, v2
	v_mov_b32_e32 v12, v2
	v_mov_b32_e32 v13, v2
	v_mov_b32_e32 v14, v2
	v_mov_b32_e32 v15, v2
	v_mov_b32_e32 v16, v2
	v_mov_b32_e32 v17, v2
	v_mov_b32_e32 v18, v2
	v_mov_b32_e32 v19, v2
	v_mov_b32_e32 v20, v2
	v_mov_b32_e32 v21, v2
	v_mov_b32_e32 v22, v2
	v_mov_b32_e32 v23, v2
	v_mov_b32_e32 v24, v2
	v_mov_b32_e32 v25, v2
	v_mov_b32_e32 v26, v2
	v_mov_b32_e32 v27, v2
	v_mov_b32_e32 v28, v2
	v_mov_b32_e32 v29, v2
	v_mov_b32_e32 v30, v2
	v_mov_b32_e32 v31, v2
	v_mov_b32_e32 v32, v2
	v_mov_b32_e32 v33, v2
	v_mov_b32_e32 v62, v2
	v_mov_b32_e32 v63, v2
	v_mov_b32_e32 v64, v2
	v_mov_b32_e32 v65, v2
	v_mov_b32_e32 v70, v2
	v_mov_b32_e32 v71, v2
	v_mov_b32_e32 v72, v2
	v_mov_b32_e32 v73, v2
	v_mov_b32_e32 v74, v2
	v_mov_b32_e32 v75, v2
	v_mov_b32_e32 v76, v2
	v_mov_b32_e32 v77, v2
	v_mov_b32_e32 v78, v2
	v_mov_b32_e32 v79, v2
	v_mov_b32_e32 v80, v2
	v_mov_b32_e32 v81, v2
	v_mov_b32_e32 v82, v2
	v_mov_b32_e32 v83, v2
	v_mov_b32_e32 v84, v2
	v_mov_b32_e32 v85, v2
	v_mov_b32_e32 v86, v2
	v_mov_b32_e32 v87, v2
	v_mov_b32_e32 v88, v2
	v_mov_b32_e32 v89, v2
	v_mov_b32_e32 v90, v2
	v_mov_b32_e32 v91, v2
	v_mov_b32_e32 v92, v2
	v_mov_b32_e32 v93, v2
	v_mov_b32_e32 v94, v2
	v_mov_b32_e32 v95, v2
	v_mov_b32_e32 v96, v2
	v_mov_b32_e32 v97, v2
	v_mov_b32_e32 v34, v2
	v_mov_b32_e32 v35, v2
	v_mov_b32_e32 v36, v2
	v_mov_b32_e32 v37, v2
	v_mov_b32_e32 v38, v2
	v_mov_b32_e32 v39, v2
	v_mov_b32_e32 v40, v2
	v_mov_b32_e32 v41, v2
	v_mov_b32_e32 v42, v2
	v_mov_b32_e32 v43, v2
	v_mov_b32_e32 v44, v2
	v_mov_b32_e32 v45, v2
	v_mov_b32_e32 v46, v2
	v_mov_b32_e32 v47, v2
	v_mov_b32_e32 v48, v2
	v_mov_b32_e32 v49, v2
	v_mov_b32_e32 v50, v2
	v_mov_b32_e32 v51, v2
	v_mov_b32_e32 v52, v2
	v_mov_b32_e32 v53, v2
	v_mov_b32_e32 v54, v2
	v_mov_b32_e32 v55, v2
	v_mov_b32_e32 v56, v2
	v_mov_b32_e32 v57, v2
	v_mov_b32_e32 v58, v2
	v_mov_b32_e32 v59, v2
	v_mov_b32_e32 v60, v2
	v_mov_b32_e32 v61, v2
	v_mov_b32_e32 v66, v2
	v_mov_b32_e32 v67, v2
	v_mov_b32_e32 v68, v2
	v_mov_b32_e32 v69, v2
	v_mov_b32_e32 v98, v2
	v_mov_b32_e32 v99, v2
	v_mov_b32_e32 v100, v2
	v_mov_b32_e32 v101, v2
	v_mov_b32_e32 v102, v2
	v_mov_b32_e32 v103, v2
	v_mov_b32_e32 v104, v2
	v_mov_b32_e32 v105, v2
	v_mov_b32_e32 v106, v2
	v_mov_b32_e32 v107, v2
	v_mov_b32_e32 v108, v2
	v_mov_b32_e32 v109, v2
	v_mov_b32_e32 v110, v2
	v_mov_b32_e32 v111, v2
	v_mov_b32_e32 v112, v2
	v_mov_b32_e32 v113, v2
	v_mov_b32_e32 v114, v2
	v_mov_b32_e32 v115, v2
	v_mov_b32_e32 v116, v2
	v_mov_b32_e32 v117, v2
	v_mov_b32_e32 v118, v2
	v_mov_b32_e32 v119, v2
	v_mov_b32_e32 v120, v2
	v_mov_b32_e32 v121, v2
	v_mov_b32_e32 v122, v2
	v_mov_b32_e32 v123, v2
	v_mov_b32_e32 v124, v2
	v_mov_b32_e32 v125, v2
	v_mov_b32_e32 v126, v2
	v_mov_b32_e32 v127, v2
	v_mov_b32_e32 v128, v2
	v_mov_b32_e32 v129, v2
	s_branch .LBB0_749
.LBB0_764:
	s_cmpk_gt_u32 s73, 0xff
	s_cbranch_scc1 .LBB0_766
	s_barrier

.LBB0_780:
	s_lshl_b32 s70, s6, 8
	s_add_i32 s8, s70, s80
	s_lshl_b32 s7, s45, 5
	v_or_b32_e32 v130, s8, v164
	s_lshl_b32 s8, s28, 8
	v_lshrrev_b32_e32 v0, 1, v163
	s_or_b32 s7, s8, s7
	v_and_or_b32 v148, v0, 24, s7
	v_ashrrev_i32_e32 v131, 31, v130
	v_lshlrev_b64 v[130:131], 10, v[130:131]
	v_ashrrev_i32_e32 v149, 31, v148
	s_load_dwordx2 s[8:9], s[4:5], 0x0
	v_lshl_add_u64 v[152:153], v[130:131], 0, v[148:149]
	s_waitcnt lgkmcnt(0)
	v_lshl_add_u64 v[130:131], v[152:153], 1, s[18:19]
	s_mov_b64 s[4:5], 0x10000000
	v_lshl_add_u64 v[150:151], v[130:131], 0, s[4:5]
	s_lshl_b32 s4, s29, 14
	v_cndmask_b32_e64 v0, 0, 1, s[38:39]
	s_add_i32 s7, s4, 0
	v_cmp_ne_u32_e64 s[10:11], 1, v0
	s_andn2_b64 vcc, exec, s[38:39]
	s_cbranch_vccnz .LBB0_782
.LBB0_782:
	s_mul_i32 s4, s2, 0x1b000
	s_add_u32 s4, s18, s4
	s_mul_hi_i32 s5, s2, 0x1b000
	s_addc_u32 s5, s19, s5
	s_add_u32 s72, s4, 0x100000
	s_addc_u32 s73, s5, 0
	s_lshl_b32 s4, s71, 2
	s_add_u32 s12, s72, s4
	s_addc_u32 s13, s73, 0
	s_ashr_i32 s4, s6, 5
	s_mul_hi_i32 s5, s4, 0x2400
	s_mulk_i32 s4, 0x2400
	s_lshl_b64 s[4:5], s[4:5], 2
	s_add_u32 s12, s12, s4
	s_addc_u32 s13, s13, s5
	v_lshl_add_u64 v[154:155], v[148:149], 2, s[12:13]
	global_load_dwordx4 v[134:137], v[154:155], off offset:16
	global_load_dwordx4 v[142:145], v[154:155], off
	global_load_dwordx4 v[168:171], v[154:155], off offset:528
	global_load_dwordx4 v[172:175], v[154:155], off offset:512
	v_lshlrev_b32_e32 v216, 2, v148
	global_load_dwordx4 v[176:179], v216, s[36:37] offset:16
	global_load_dwordx4 v[180:183], v216, s[36:37]
	global_load_dwordx4 v[184:187], v216, s[36:37] offset:528
	global_load_dwordx4 v[188:191], v216, s[36:37] offset:512
	s_and_b64 vcc, exec, s[30:31]
	s_cbranch_vccz .Lcab_nomods
	v_readlane_b32 s12, v255, 5
	v_readlane_b32 s13, v255, 4
	s_add_u32 s98, s72, s12
	s_addc_u32 s99, s73, 0
	s_lshl_b32 s13, s13, 2
	s_add_u32 s98, s98, s13
	s_addc_u32 s99, s99, 0
	s_add_u32 s98, s98, s4
	s_addc_u32 s99, s99, s5
	s_add_u32 s100, s98, 0x1000
	s_addc_u32 s101, s99, 0
	global_load_dwordx4 v[192:195], v216, s[100:101] offset:16
	global_load_dwordx4 v[196:199], v216, s[100:101]
	global_load_dwordx4 v[200:203], v216, s[100:101] offset:528
	global_load_dwordx4 v[204:207], v216, s[100:101] offset:512
	global_load_dwordx4 v[208:211], v216, s[98:99]
	global_load_dwordx4 v[212:215], v216, s[98:99] offset:16
	global_load_dwordx4 v[220:223], v216, s[98:99] offset:512
	global_load_dwordx4 v[224:227], v216, s[98:99] offset:528
.Lcab_nomods:
	v_and_b32_e32 v0, 63, v163
	v_lshlrev_b32_e32 v130, 4, v0
	s_mov_b64 s[12:13], -1
	s_and_b64 vcc, exec, s[38:39]
	v_add_u32_e32 v165, s7, v130
	s_lshl_b32 s99, s29, 10
	v_add_u32_e32 v235, s99, v130
	v_add_u32_e32 v236, 0x10000, v235
	v_add_u32_e32 v237, 0x20000, v235
	s_cbranch_vccz .LBB0_784
	s_waitcnt vmcnt(0)
	ds_read_b128 v[130:133], v236 offset:0
	s_mov_b64 s[12:13], 0
	s_waitcnt lgkmcnt(0)
	v_lshlrev_b32_e32 v138, 16, v130
	v_and_b32_e32 v139, 0xffff0000, v130
	v_lshlrev_b32_e32 v140, 16, v131
	v_and_b32_e32 v141, 0xffff0000, v131
	v_lshlrev_b32_e32 v130, 16, v132
	v_and_b32_e32 v131, 0xffff0000, v132
	v_lshlrev_b32_e32 v132, 16, v133
	v_and_b32_e32 v133, 0xffff0000, v133

.LBB0_788:
	s_and_b64 vcc, exec, s[10:11]
	s_mov_b64 s[12:13], -1
	s_cbranch_vccnz .LBB0_790
	ds_read_b128 v[122:125], v236 offset:8192
	s_waitcnt lgkmcnt(0)
	v_lshlrev_b32_e32 v126, 16, v122
	v_and_b32_e32 v127, 0xffff0000, v122
	v_lshlrev_b32_e32 v128, 16, v123
	v_and_b32_e32 v129, 0xffff0000, v123
	v_lshlrev_b32_e32 v122, 16, v124
	v_and_b32_e32 v123, 0xffff0000, v124
	v_lshlrev_b32_e32 v124, 16, v125
	v_and_b32_e32 v125, 0xffff0000, v125
	s_cbranch_execz .LBB0_791
	s_branch .LBB0_792

.LBB0_794:
	s_and_b64 vcc, exec, s[10:11]
	s_mov_b64 s[12:13], -1
	s_cbranch_vccnz .LBB0_796
	ds_read_b128 v[114:117], v236 offset:16384
	s_waitcnt lgkmcnt(0)
	v_lshlrev_b32_e32 v118, 16, v114
	v_and_b32_e32 v119, 0xffff0000, v114
	v_lshlrev_b32_e32 v120, 16, v115
	v_and_b32_e32 v121, 0xffff0000, v115
	v_lshlrev_b32_e32 v114, 16, v116
	v_and_b32_e32 v115, 0xffff0000, v116
	v_lshlrev_b32_e32 v116, 16, v117
	v_and_b32_e32 v117, 0xffff0000, v117
	s_cbranch_execz .LBB0_797
	s_branch .LBB0_798

.LBB0_800:
	s_and_b64 vcc, exec, s[10:11]
	s_mov_b64 s[12:13], -1
	s_cbranch_vccnz .LBB0_802
	ds_read_b128 v[106:109], v236 offset:24576
	s_waitcnt lgkmcnt(0)
	v_lshlrev_b32_e32 v110, 16, v106
	v_and_b32_e32 v111, 0xffff0000, v106
	v_lshlrev_b32_e32 v112, 16, v107
	v_and_b32_e32 v113, 0xffff0000, v107
	v_lshlrev_b32_e32 v106, 16, v108
	v_and_b32_e32 v107, 0xffff0000, v108
	v_lshlrev_b32_e32 v108, 16, v109
	v_and_b32_e32 v109, 0xffff0000, v109
	s_cbranch_execz .LBB0_803
	s_branch .LBB0_804

.LBB0_806:
	s_and_b64 vcc, exec, s[10:11]
	s_mov_b64 s[12:13], -1
	s_cbranch_vccnz .LBB0_808
	ds_read_b128 v[98:101], v237 offset:0
	s_mov_b64 s[12:13], 0
	s_waitcnt lgkmcnt(0)
	v_lshlrev_b32_e32 v102, 16, v98
	v_and_b32_e32 v103, 0xffff0000, v98
	v_lshlrev_b32_e32 v104, 16, v99
	v_and_b32_e32 v105, 0xffff0000, v99
	v_lshlrev_b32_e32 v98, 16, v100
	v_and_b32_e32 v99, 0xffff0000, v100
	v_lshlrev_b32_e32 v100, 16, v101
	v_and_b32_e32 v101, 0xffff0000, v101

.LBB0_812:
	s_and_b64 vcc, exec, s[10:11]
	s_mov_b64 s[12:13], -1
	s_cbranch_vccnz .LBB0_814
	ds_read_b128 v[90:93], v235 offset:8192
	s_waitcnt lgkmcnt(0)
	v_lshlrev_b32_e32 v94, 16, v90
	v_and_b32_e32 v95, 0xffff0000, v90
	v_lshlrev_b32_e32 v96, 16, v91
	v_and_b32_e32 v97, 0xffff0000, v91
	v_lshlrev_b32_e32 v90, 16, v92
	v_and_b32_e32 v91, 0xffff0000, v92
	v_lshlrev_b32_e32 v92, 16, v93
	v_and_b32_e32 v93, 0xffff0000, v93
	s_cbranch_execz .LBB0_815
	s_branch .LBB0_816

.LBB0_818:
	s_and_b64 vcc, exec, s[10:11]
	s_mov_b64 s[12:13], -1
	s_cbranch_vccnz .LBB0_820
	ds_read_b128 v[82:85], v237 offset:16384
	s_waitcnt lgkmcnt(0)
	v_lshlrev_b32_e32 v86, 16, v82
	v_and_b32_e32 v87, 0xffff0000, v82
	v_lshlrev_b32_e32 v88, 16, v83
	v_and_b32_e32 v89, 0xffff0000, v83
	v_lshlrev_b32_e32 v82, 16, v84
	v_and_b32_e32 v83, 0xffff0000, v84
	v_lshlrev_b32_e32 v84, 16, v85
	v_and_b32_e32 v85, 0xffff0000, v85
	s_cbranch_execz .LBB0_821
	s_branch .LBB0_822

.LBB0_824:
	s_and_b64 vcc, exec, s[10:11]
	s_mov_b64 s[12:13], -1
	s_cbranch_vccnz .LBB0_826
	ds_read_b128 v[74:77], v237 offset:24576
	s_waitcnt lgkmcnt(0)
	v_lshlrev_b32_e32 v78, 16, v74
	v_and_b32_e32 v79, 0xffff0000, v74
	v_lshlrev_b32_e32 v80, 16, v75
	v_and_b32_e32 v81, 0xffff0000, v75
	v_lshlrev_b32_e32 v74, 16, v76
	v_and_b32_e32 v75, 0xffff0000, v76
	v_lshlrev_b32_e32 v76, 16, v77
	v_and_b32_e32 v77, 0xffff0000, v77
	s_cbranch_execz .LBB0_827
	s_branch .LBB0_828

.LBB0_830:
	v_mov_b64_e32 v[70:71], v[168:169]
	v_mov_b64_e32 v[72:73], v[170:171]
	v_mov_b64_e32 v[78:79], v[172:173]
	v_mov_b64_e32 v[80:81], v[174:175]
	s_and_b64 vcc, exec, s[10:11]
	s_mov_b64 s[12:13], -1
	s_cbranch_vccnz .LBB0_832
	ds_read_b128 v[62:65], v235 offset:16384
	s_mov_b64 s[12:13], 0
	s_waitcnt lgkmcnt(0)
	v_lshlrev_b32_e32 v74, 16, v62
	v_and_b32_e32 v75, 0xffff0000, v62
	v_lshlrev_b32_e32 v76, 16, v63
	v_and_b32_e32 v77, 0xffff0000, v63
	v_lshlrev_b32_e32 v62, 16, v64
	v_and_b32_e32 v63, 0xffff0000, v64
	v_lshlrev_b32_e32 v64, 16, v65
	v_and_b32_e32 v65, 0xffff0000, v65

.LBB0_836:
	s_and_b64 vcc, exec, s[10:11]
	s_mov_b64 s[12:13], -1
	s_cbranch_vccnz .LBB0_838
	ds_read_b128 v[58:61], v235 offset:24576
	s_waitcnt lgkmcnt(0)
	v_lshlrev_b32_e32 v62, 16, v58
	v_and_b32_e32 v63, 0xffff0000, v58
	v_lshlrev_b32_e32 v64, 16, v59
	v_and_b32_e32 v65, 0xffff0000, v59
	v_lshlrev_b32_e32 v58, 16, v60
	v_and_b32_e32 v59, 0xffff0000, v60
	v_lshlrev_b32_e32 v60, 16, v61
	v_and_b32_e32 v61, 0xffff0000, v61
	s_cbranch_execz .LBB0_839
	s_branch .LBB0_840

.LBB0_842:
	s_and_b64 vcc, exec, s[10:11]
	s_mov_b64 s[12:13], -1
	s_cbranch_vccnz .LBB0_844
	ds_read_b128 v[50:53], v236 offset:32768
	s_waitcnt lgkmcnt(0)
	v_lshlrev_b32_e32 v54, 16, v50
	v_and_b32_e32 v55, 0xffff0000, v50
	v_lshlrev_b32_e32 v56, 16, v51
	v_and_b32_e32 v57, 0xffff0000, v51
	v_lshlrev_b32_e32 v50, 16, v52
	v_and_b32_e32 v51, 0xffff0000, v52
	v_lshlrev_b32_e32 v52, 16, v53
	v_and_b32_e32 v53, 0xffff0000, v53
	s_cbranch_execz .LBB0_845
	s_branch .LBB0_846

.LBB0_848:
	s_and_b64 vcc, exec, s[10:11]
	s_mov_b64 s[12:13], -1
	s_cbranch_vccnz .LBB0_850
	ds_read_b128 v[42:45], v236 offset:40960
	s_waitcnt lgkmcnt(0)
	v_lshlrev_b32_e32 v46, 16, v42
	v_and_b32_e32 v47, 0xffff0000, v42
	v_lshlrev_b32_e32 v48, 16, v43
	v_and_b32_e32 v49, 0xffff0000, v43
	v_lshlrev_b32_e32 v42, 16, v44
	v_and_b32_e32 v43, 0xffff0000, v44
	v_lshlrev_b32_e32 v44, 16, v45
	v_and_b32_e32 v45, 0xffff0000, v45
	s_cbranch_execz .LBB0_851
	s_branch .LBB0_852

.LBB0_854:
	s_and_b64 vcc, exec, s[10:11]
	s_mov_b64 s[12:13], -1
	s_cbranch_vccnz .LBB0_856
	ds_read_b128 v[34:37], v236 offset:49152
	s_mov_b64 s[12:13], 0
	s_waitcnt lgkmcnt(0)
	v_lshlrev_b32_e32 v38, 16, v34
	v_and_b32_e32 v39, 0xffff0000, v34
	v_lshlrev_b32_e32 v40, 16, v35
	v_and_b32_e32 v41, 0xffff0000, v35
	v_lshlrev_b32_e32 v34, 16, v36
	v_and_b32_e32 v35, 0xffff0000, v36
	v_lshlrev_b32_e32 v36, 16, v37
	v_and_b32_e32 v37, 0xffff0000, v37

.LBB0_860:
	s_and_b64 vcc, exec, s[10:11]
	s_mov_b64 s[12:13], -1
	s_cbranch_vccnz .LBB0_862
	ds_read_b128 v[26:29], v236 offset:57344
	s_waitcnt lgkmcnt(0)
	v_lshlrev_b32_e32 v30, 16, v26
	v_and_b32_e32 v31, 0xffff0000, v26
	v_lshlrev_b32_e32 v32, 16, v27
	v_and_b32_e32 v33, 0xffff0000, v27
	v_lshlrev_b32_e32 v26, 16, v28
	v_and_b32_e32 v27, 0xffff0000, v28
	v_lshlrev_b32_e32 v28, 16, v29
	v_and_b32_e32 v29, 0xffff0000, v29
	s_cbranch_execz .LBB0_863
	s_branch .LBB0_864

.LBB0_866:
	s_and_b64 vcc, exec, s[10:11]
	s_mov_b64 s[12:13], -1
	s_cbranch_vccnz .LBB0_868
	ds_read_b128 v[18:21], v235 offset:32768
	s_waitcnt lgkmcnt(0)
	v_lshlrev_b32_e32 v22, 16, v18
	v_and_b32_e32 v23, 0xffff0000, v18
	v_lshlrev_b32_e32 v24, 16, v19
	v_and_b32_e32 v25, 0xffff0000, v19
	v_lshlrev_b32_e32 v18, 16, v20
	v_and_b32_e32 v19, 0xffff0000, v20
	v_lshlrev_b32_e32 v20, 16, v21
	v_and_b32_e32 v21, 0xffff0000, v21
	s_cbranch_execz .LBB0_869
	s_branch .LBB0_870

.LBB0_872:
	s_and_b64 vcc, exec, s[10:11]
	s_mov_b64 s[10:11], -1
	s_cbranch_vccnz .LBB0_874
	ds_read_b128 v[10:13], v235 offset:40960
	s_waitcnt lgkmcnt(0)
	v_lshlrev_b32_e32 v14, 16, v10
	v_and_b32_e32 v15, 0xffff0000, v10
	v_lshlrev_b32_e32 v16, 16, v11
	v_and_b32_e32 v17, 0xffff0000, v11
	v_lshlrev_b32_e32 v10, 16, v12
	v_and_b32_e32 v11, 0xffff0000, v12
	v_lshlrev_b32_e32 v12, 16, v13
	v_and_b32_e32 v13, 0xffff0000, v13
	s_cbranch_execz .LBB0_875
	s_branch .LBB0_876

	.amdhsa_kernel _ZN12_GLOBAL__N_12mkENS_6ParamsE
		.amdhsa_group_segment_fixed_size 16384
		.amdhsa_private_segment_fixed_size 0
		.amdhsa_kernarg_size 488
		.amdhsa_user_sgpr_count 2
		.amdhsa_user_sgpr_dispatch_ptr 0
		.amdhsa_user_sgpr_queue_ptr 0
		.amdhsa_user_sgpr_kernarg_segment_ptr 1
		.amdhsa_user_sgpr_dispatch_id 0
		.amdhsa_user_sgpr_kernarg_preload_length 0
		.amdhsa_user_sgpr_kernarg_preload_offset 0
		.amdhsa_user_sgpr_private_segment_size 0
		.amdhsa_uses_dynamic_stack 0
		.amdhsa_enable_private_segment 0
		.amdhsa_system_sgpr_workgroup_id_x 1
		.amdhsa_system_sgpr_workgroup_id_y 0
		.amdhsa_system_sgpr_workgroup_id_z 0
		.amdhsa_system_sgpr_workgroup_info 0
		.amdhsa_system_vgpr_workitem_id 2
		.amdhsa_next_free_vgpr 256
		.amdhsa_next_free_sgpr 102
		.amdhsa_accum_offset 256
		.amdhsa_reserve_vcc 1
		.amdhsa_float_round_mode_32 0
		.amdhsa_float_round_mode_16_64 0
		.amdhsa_float_denorm_mode_32 3
		.amdhsa_float_denorm_mode_16_64 3
		.amdhsa_dx10_clamp 1
		.amdhsa_ieee_mode 1
		.amdhsa_fp16_overflow 0
		.amdhsa_tg_split 0
		.amdhsa_exception_fp_ieee_invalid_op 0
		.amdhsa_exception_fp_denorm_src 0
		.amdhsa_exception_fp_ieee_div_zero 0
		.amdhsa_exception_fp_ieee_overflow 0
		.amdhsa_exception_fp_ieee_underflow 0
		.amdhsa_exception_fp_ieee_inexact 0
		.amdhsa_exception_int_div_zero 0
	.end_amdhsa_kernel

amdhsa.kernels:
  - .agpr_count:     0
    .args:
      - .offset:         0
        .size:           232
        .value_kind:     by_value
      - .offset:         232
        .size:           4
        .value_kind:     hidden_block_count_x
      - .offset:         236
        .size:           4
        .value_kind:     hidden_block_count_y
      - .offset:         240
        .size:           4
        .value_kind:     hidden_block_count_z
      - .offset:         244
        .size:           2
        .value_kind:     hidden_group_size_x
      - .offset:         246
        .size:           2
        .value_kind:     hidden_group_size_y
      - .offset:         248
        .size:           2
        .value_kind:     hidden_group_size_z
      - .offset:         250
        .size:           2
        .value_kind:     hidden_remainder_x
      - .offset:         252
        .size:           2
        .value_kind:     hidden_remainder_y
      - .offset:         254
        .size:           2
        .value_kind:     hidden_remainder_z
      - .offset:         272
        .size:           8
        .value_kind:     hidden_global_offset_x
      - .offset:         280
        .size:           8
        .value_kind:     hidden_global_offset_y
      - .offset:         288
        .size:           8
        .value_kind:     hidden_global_offset_z
      - .offset:         296
        .size:           2
        .value_kind:     hidden_grid_dims
      - .offset:         320
        .size:           8
        .value_kind:     hidden_multigrid_sync_arg
      - .offset:         352
        .size:           4
        .value_kind:     hidden_dynamic_lds_size
    .group_segment_fixed_size: 16384
    .kernarg_segment_align: 8
    .kernarg_segment_size: 488
    .language:       OpenCL C
    .language_version:
      - 2
      - 0
    .max_flat_workgroup_size: 512
    .name:           _ZN12_GLOBAL__N_12mkENS_6ParamsE
    .private_segment_fixed_size: 0
    .sgpr_count:     108
    .sgpr_spill_count: 112
    .symbol:         _ZN12_GLOBAL__N_12mkENS_6ParamsE.kd
    .uniform_work_group_size: 1
    .uses_dynamic_stack: false
    .vgpr_count:     256
    .vgpr_spill_count: 0
    .wavefront_size: 64
